# P12 rowpass_last: post-norm gain and the 4 gate vectors staged in LDS once; per-group fetches are ds_reads so their waits no longer cover the previous store
# speedup vs baseline: 1.0099x; 1.0039x over previous
.LBB0_919:
	s_cmp_lt_i32 s24, 13
	s_cselect_b64 s[0:1], -1, 0
	s_cmp_gt_i32 s25, 12
	s_cselect_b64 s[2:3], -1, 0
	s_and_b64 s[0:1], s[0:1], s[2:3]
	s_andn2_b64 vcc, exec, s[0:1]
	s_cbranch_vccnz .LBB0_923
	s_add_u32 s4, s18, 0x8000
	s_addc_u32 s0, s19, 0
	s_cmpk_gt_i32 s34, 0x1fff
	s_waitcnt vmcnt(0)
	v_mbcnt_lo_u32_b32 v0, -1, 0
	v_mbcnt_hi_u32_b32 v0, -1, v0
	s_cbranch_scc1 .LBB0_923
	v_lshlrev_b32_e32 v98, 4, v0
	v_lshlrev_b32_e32 v99, 3, v0
	v_mbcnt_lo_u32_b32 v0, -1, 0
	v_mbcnt_hi_u32_b32 v0, -1, v0
	v_and_b32_e32 v1, 64, v0
	v_add_u32_e32 v1, 64, v1
	v_xor_b32_e32 v2, 1, v0
	v_cmp_lt_i32_e32 vcc, v2, v1
	s_add_u32 s26, s74, 0x118000
	s_addc_u32 s27, s75, 0
	v_cndmask_b32_e32 v2, v0, v2, vcc
	v_lshlrev_b32_e32 v100, 2, v2
	v_xor_b32_e32 v2, 2, v0
	v_cmp_lt_i32_e32 vcc, v2, v1
	s_ashr_i32 s35, s34, 31
	s_ashr_i32 s73, s72, 31
	v_cndmask_b32_e32 v2, v0, v2, vcc
	v_lshlrev_b32_e32 v101, 2, v2
	v_xor_b32_e32 v2, 4, v0
	v_cmp_lt_i32_e32 vcc, v2, v1
	v_readlane_b32 s12, v250, 0
	s_and_b32 s5, s0, 0xffff
	v_cndmask_b32_e32 v2, v0, v2, vcc
	v_lshlrev_b32_e32 v102, 2, v2
	v_xor_b32_e32 v2, 8, v0
	v_cmp_lt_i32_e32 vcc, v2, v1
	s_lshl_b64 s[20:21], s[34:35], 13
	s_lshl_b64 s[22:23], s[72:73], 13
	v_cndmask_b32_e32 v2, v0, v2, vcc
	v_lshlrev_b32_e32 v103, 2, v2
	v_xor_b32_e32 v2, 16, v0
	v_cmp_lt_i32_e32 vcc, v2, v1
	s_lshl_b64 s[0:1], s[34:35], 14
	v_readlane_b32 s14, v250, 2
	v_cndmask_b32_e32 v2, v0, v2, vcc
	v_lshlrev_b32_e32 v104, 2, v2
	v_xor_b32_e32 v2, 32, v0
	v_cmp_lt_i32_e32 vcc, v2, v1
	s_mov_b32 s3, 0x20000
	v_readlane_b32 s15, v250, 3
	v_cndmask_b32_e32 v0, v0, v2, vcc
	s_add_u32 s28, s14, s0
	s_movk_i32 s10, 0x4000
	s_movk_i32 s6, 0x4000
	s_mov_b32 s7, s3
	v_lshlrev_b32_e32 v105, 2, v0
	s_addc_u32 s29, s15, s1
	s_lshl_b64 s[24:25], s[72:73], 14
	s_movk_i32 s2, 0x2000
	s_movk_i32 s30, 0x200
	s_movk_i32 s31, 0x400
	s_movk_i32 s33, 0x600
	s_movk_i32 s35, 0x800
	s_movk_i32 s36, 0xa00
	s_movk_i32 s37, 0xc00
	s_movk_i32 s38, 0xe00
	s_movk_i32 s39, 0x1000
	s_movk_i32 s40, 0x1200
	s_movk_i32 s41, 0x1400
	s_movk_i32 s42, 0x1600
	s_movk_i32 s43, 0x1800
	s_movk_i32 s44, 0x1a00
	s_movk_i32 s45, 0x1c00
	s_movk_i32 s46, 0x1e00
	v_mov_b32_e32 v106, 0x358637bd
	s_mov_b32 s47, 0xf800000
	v_mov_b32_e32 v107, 0x260
	s_movk_i32 s48, 0x2400
	s_movk_i32 s49, 0x2800
	s_movk_i32 s50, 0x2c00
	s_movk_i32 s51, 0x3000
	s_movk_i32 s52, 0x3400
	s_movk_i32 s53, 0x3800
	s_movk_i32 s54, 0x3c00
	v_readlane_b32 s55, v250, 38
	v_readlane_b32 s56, v250, 39
	v_readlane_b32 s13, v250, 1
	v_readlane_b32 s57, v250, 14
	s_movk_i32 s58, 0x2000
	s_add_u32 s60, s26, 0x8000
	s_addc_u32 s61, s27, 0
	s_and_b32 s61, s61, 0xffff
	s_movk_i32 s62, 0x4000
	s_mov_b32 s63, 0x20000
	s_lshl_b32 s57, s57, 10
	v_add_u32_e32 v174, s57, v98
	v_add_u32_e32 v175, 0x10000, v174
	buffer_load_dwordx4 v[176:179], v174, s[4:7], 0 offen
	buffer_load_dwordx4 v[180:183], v174, s[4:7], s58 offen
	buffer_load_dwordx4 v[184:187], v174, s[60:63], 0 offen
	buffer_load_dwordx4 v[188:191], v174, s[60:63], s58 offen
	s_add_u32 s60, s60, 0x24000
	s_addc_u32 s61, s61, 0
	buffer_load_dwordx4 v[192:195], v174, s[60:63], 0 offen
	buffer_load_dwordx4 v[196:199], v174, s[60:63], s58 offen
	s_add_u32 s60, s60, 0x24000
	s_addc_u32 s61, s61, 0
	buffer_load_dwordx4 v[200:203], v174, s[60:63], 0 offen
	buffer_load_dwordx4 v[204:207], v174, s[60:63], s58 offen
	s_add_u32 s60, s60, 0x24000
	s_addc_u32 s61, s61, 0
	buffer_load_dwordx4 v[208:211], v174, s[60:63], 0 offen
	buffer_load_dwordx4 v[212:215], v174, s[60:63], s58 offen
	s_waitcnt vmcnt(0)
	ds_write_b128 v174, v[176:179]
	ds_write_b128 v174, v[180:183] offset:8192
	ds_write_b128 v174, v[184:187] offset:16384
	ds_write_b128 v174, v[188:191] offset:24576
	ds_write_b128 v174, v[192:195] offset:32768
	ds_write_b128 v174, v[196:199] offset:40960
	ds_write_b128 v174, v[200:203] offset:49152
	ds_write_b128 v174, v[204:207] offset:57344
	ds_write_b128 v175, v[208:211]
	ds_write_b128 v175, v[212:215] offset:8192
	s_waitcnt lgkmcnt(0)
	s_barrier
.LBB0_922:
	s_ashr_i32 s0, s34, 31
	s_lshr_b32 s0, s0, 21
	s_add_i32 s0, s34, s0
	s_ashr_i32 s1, s0, 11
	s_lshl_b32 s57, s1, 14
	s_add_i32 s57, s57, 0x4000
	v_add_u32_e32 v174, s57, v98
	s_add_u32 s0, s84, s20
	s_mul_hi_i32 s9, s1, 0x24000
	s_mul_i32 s12, s1, 0x24000
	s_addc_u32 s1, s85, s21
	s_and_b32 s1, s1, 0xffff
	ds_read_b128 v[0:3], v98
	buffer_load_dwordx2 v[10:11], v99, s[0:3], 0 offen nt
	buffer_load_dwordx2 v[8:9], v99, s[0:3], s30 offen nt
	buffer_load_dwordx2 v[12:13], v99, s[0:3], s31 offen nt
	buffer_load_dwordx2 v[18:19], v99, s[0:3], s33 offen nt
	buffer_load_dwordx2 v[20:21], v99, s[0:3], s35 offen nt
	buffer_load_dwordx2 v[22:23], v99, s[0:3], s36 offen nt
	buffer_load_dwordx2 v[24:25], v99, s[0:3], s37 offen nt
	buffer_load_dwordx2 v[28:29], v99, s[0:3], s38 offen nt
	buffer_load_dwordx2 v[32:33], v99, s[0:3], s39 offen nt
	buffer_load_dwordx2 v[34:35], v99, s[0:3], s40 offen nt
	buffer_load_dwordx2 v[36:37], v99, s[0:3], s41 offen nt
	buffer_load_dwordx2 v[112:113], v99, s[0:3], s42 offen nt
	buffer_load_dwordx2 v[114:115], v99, s[0:3], s43 offen nt
	buffer_load_dwordx2 v[116:117], v99, s[0:3], s44 offen nt
	buffer_load_dwordx2 v[118:119], v99, s[0:3], s45 offen nt
	buffer_load_dwordx2 v[120:121], v99, s[0:3], s46 offen nt
	s_add_u32 s16, s55, s20
	s_addc_u32 s0, s56, s21
	s_add_u32 s1, s26, s12
	s_addc_u32 s9, s27, s9
	s_add_u32 s12, s1, 0x8000
	s_addc_u32 s1, s9, 0
	s_mov_b32 s18, s2
	s_mov_b32 s19, s3
	s_mov_b32 s14, s10
	s_mov_b32 s15, s3
	s_and_b32 s17, s0, 0xffff
	s_and_b32 s13, s1, 0xffff
	buffer_load_dwordx2 v[122:123], v99, s[16:19], 0 offen nt
	buffer_load_dwordx2 v[96:97], v99, s[16:19], s30 offen nt
	buffer_load_dwordx2 v[88:89], v99, s[16:19], s31 offen nt
	buffer_load_dwordx2 v[80:81], v99, s[16:19], s33 offen nt
	buffer_load_dwordx2 v[72:73], v99, s[16:19], s35 offen nt
	buffer_load_dwordx2 v[66:67], v99, s[16:19], s36 offen nt
	buffer_load_dwordx2 v[58:59], v99, s[16:19], s37 offen nt
	buffer_load_dwordx2 v[52:53], v99, s[16:19], s38 offen nt
	buffer_load_dwordx2 v[46:47], v99, s[16:19], s39 offen nt
	buffer_load_dwordx2 v[38:39], v99, s[16:19], s40 offen nt
	buffer_load_dwordx2 v[30:31], v99, s[16:19], s41 offen nt
	buffer_load_dwordx2 v[26:27], v99, s[16:19], s42 offen nt
	buffer_load_dwordx2 v[16:17], v99, s[16:19], s43 offen nt
	buffer_load_dwordx2 v[14:15], v99, s[16:19], s44 offen nt
	s_waitcnt lgkmcnt(0)
	buffer_load_dwordx2 v[6:7], v99, s[16:19], s45 offen nt
	buffer_load_dwordx2 v[4:5], v99, s[16:19], s46 offen nt
	ds_read_b128 v[108:111], v174
	s_mov_b32 s8, s28
	s_mov_b32 s11, s3
	s_and_b32 s9, s29, 0xffff
	s_add_i32 s34, s34, s72
	s_add_u32 s20, s20, s22
	s_addc_u32 s21, s21, s23
	s_add_u32 s28, s28, s24
	s_addc_u32 s29, s29, s25
	s_cmpk_lt_i32 s34, 0x2000
	s_waitcnt vmcnt(31)
	v_and_b32_e32 v125, 0xffff0000, v11
	v_lshlrev_b32_e32 v124, 16, v11
	s_waitcnt vmcnt(30)
	v_and_b32_e32 v129, 0xffff0000, v9
	v_and_b32_e32 v128, 0xffff0000, v8
	s_waitcnt vmcnt(28)
	v_lshlrev_b32_e32 v91, 16, v18
	v_lshlrev_b32_e32 v84, 16, v19
	v_and_b32_e32 v85, 0xffff0000, v19
	v_lshlrev_b32_e32 v127, 16, v9
	v_lshlrev_b32_e32 v126, 16, v8
	s_waitcnt vmcnt(22)
	v_lshlrev_b32_e32 v51, 16, v35
	v_lshlrev_b32_e32 v50, 16, v34
	v_and_b32_e32 v49, 0xffff0000, v35
	v_and_b32_e32 v48, 0xffff0000, v34
	s_waitcnt vmcnt(20)
	v_lshlrev_b32_e32 v34, 16, v113
	v_and_b32_e32 v35, 0xffff0000, v113
	v_and_b32_e32 v113, 0xffff0000, v10
	v_lshlrev_b32_e32 v44, 16, v37
	v_and_b32_e32 v45, 0xffff0000, v37
	v_lshlrev_b32_e32 v41, 16, v112
	v_and_b32_e32 v37, 0xffff0000, v112
	s_waitcnt vmcnt(17)
	v_and_b32_e32 v19, 0xffff0000, v118
	s_waitcnt vmcnt(16)
	v_and_b32_e32 v11, 0xffff0000, v120
	v_lshlrev_b32_e32 v112, 16, v10
	v_mul_f32_e32 v10, v125, v125
	v_mul_f32_e32 v40, v113, v113
	v_and_b32_e32 v93, 0xffff0000, v12
	v_and_b32_e32 v95, 0xffff0000, v13
	v_and_b32_e32 v87, 0xffff0000, v18
	v_lshlrev_b32_e32 v65, 16, v28
	v_and_b32_e32 v63, 0xffff0000, v28
	v_lshlrev_b32_e32 v60, 16, v29
	v_and_b32_e32 v61, 0xffff0000, v29
	v_lshlrev_b32_e32 v57, 16, v33
	v_lshlrev_b32_e32 v56, 16, v32
	v_and_b32_e32 v55, 0xffff0000, v33
	v_and_b32_e32 v54, 0xffff0000, v32
	v_lshlrev_b32_e32 v33, 16, v115
	v_lshlrev_b32_e32 v32, 16, v114
	v_and_b32_e32 v29, 0xffff0000, v115
	v_and_b32_e32 v28, 0xffff0000, v114
	v_lshlrev_b32_e32 v18, 16, v118
	v_pk_mul_f32 v[114:115], v[128:129], v[128:129]
	v_mov_b32_e32 v137, v91
	v_mul_f32_e32 v90, v45, v45
	v_mul_f32_e32 v136, v19, v19
	v_pk_fma_f32 v[144:145], v[124:125], v[124:125], v[10:11] op_sel_hi:[1,1,0]
	v_pk_fma_f32 v[150:151], v[112:113], v[112:113], v[40:41] op_sel_hi:[1,1,0]
	v_lshlrev_b32_e32 v92, 16, v12
	v_lshlrev_b32_e32 v94, 16, v13
	v_lshlrev_b32_e32 v42, 16, v36
	v_and_b32_e32 v43, 0xffff0000, v36
	v_lshlrev_b32_e32 v13, 16, v120
	v_mul_f32_e32 v12, v93, v93
	v_mul_f32_e32 v36, v95, v95
	v_pk_fma_f32 v[114:115], v[126:127], v[126:127], v[114:115]
	v_pk_fma_f32 v[158:159], v[44:45], v[44:45], v[90:91] op_sel_hi:[1,1,0]
	v_pk_fma_f32 v[160:161], v[18:19], v[18:19], v[136:137] op_sel_hi:[1,1,0]
	v_mov_b32_e32 v90, v150
	v_mov_b32_e32 v136, v144
	v_mul_f32_e32 v140, v87, v87
	v_mul_f32_e32 v142, v84, v84
	v_mul_f32_e32 v164, v85, v85
	v_pk_fma_f32 v[146:147], v[92:93], v[92:93], v[12:13] op_sel_hi:[1,1,0]
	v_pk_fma_f32 v[148:149], v[94:95], v[94:95], v[36:37] op_sel_hi:[1,1,0]
	v_pk_add_f32 v[144:145], v[150:151], v[144:145]
	v_pk_add_f32 v[114:115], v[114:115], v[114:115] op_sel:[0,1] op_sel_hi:[1,0]
	v_pk_mul_f32 v[136:137], v[90:91], v[136:137]
	v_and_b32_e32 v79, 0xffff0000, v21
	v_and_b32_e32 v78, 0xffff0000, v20
	v_mov_b32_e32 v147, v142
	v_mov_b32_e32 v149, v164
	v_mov_b32_e32 v115, v140
	v_mov_b32_e32 v145, v137
	v_lshlrev_b32_e32 v83, 16, v21
	v_lshlrev_b32_e32 v82, 16, v20
	v_lshlrev_b32_e32 v77, 16, v23
	v_lshlrev_b32_e32 v76, 16, v22
	v_and_b32_e32 v75, 0xffff0000, v23
	v_and_b32_e32 v74, 0xffff0000, v22
	v_lshlrev_b32_e32 v68, 16, v24
	v_and_b32_e32 v69, 0xffff0000, v24
	v_lshlrev_b32_e32 v70, 16, v25
	v_and_b32_e32 v71, 0xffff0000, v25
	v_lshlrev_b32_e32 v25, 16, v117
	v_lshlrev_b32_e32 v24, 16, v116
	v_and_b32_e32 v23, 0xffff0000, v117
	v_and_b32_e32 v22, 0xffff0000, v116
	v_pk_mul_f32 v[116:117], v[78:79], v[78:79]
	v_pk_add_f32 v[146:147], v[146:147], v[148:149]
	v_pk_add_f32 v[114:115], v[144:145], v[114:115]
	v_and_b32_e32 v21, 0xffff0000, v119
	v_pk_fma_f32 v[116:117], v[82:83], v[82:83], v[116:117]
	v_pk_add_f32 v[114:115], v[114:115], v[146:147]
	v_lshlrev_b32_e32 v20, 16, v119
	v_pk_mul_f32 v[118:119], v[74:75], v[74:75]
	v_mul_f32_e32 v64, v71, v71
	v_mov_b32_e32 v139, v65
	v_mul_f32_e32 v138, v21, v21
	v_pk_add_f32 v[116:117], v[116:117], v[116:117] op_sel:[0,1] op_sel_hi:[1,0]
	v_pk_add_f32 v[114:115], v[114:115], v[114:115] op_sel:[0,1] op_sel_hi:[1,0]
	v_mul_f32_e32 v62, v69, v69
	v_pk_fma_f32 v[118:119], v[76:77], v[76:77], v[118:119]
	v_pk_fma_f32 v[154:155], v[70:71], v[70:71], v[64:65] op_sel_hi:[1,1,0]
	v_pk_fma_f32 v[162:163], v[20:21], v[20:21], v[138:139] op_sel_hi:[1,1,0]
	v_mov_b32_e32 v138, v116
	v_mov_b32_e32 v64, v114
	v_mul_f32_e32 v165, v63, v63
	v_mul_f32_e32 v166, v60, v60
	v_mul_f32_e32 v167, v61, v61
	v_pk_fma_f32 v[152:153], v[68:69], v[68:69], v[62:63] op_sel_hi:[1,1,0]
	v_pk_add_f32 v[118:119], v[118:119], v[118:119] op_sel:[0,1] op_sel_hi:[1,0]
	v_pk_add_f32 v[114:115], v[114:115], v[116:117]
	v_pk_mul_f32 v[116:117], v[64:65], v[138:139]
	v_mov_b32_e32 v153, v166
	v_mov_b32_e32 v155, v167
	v_mov_b32_e32 v119, v165
	v_mov_b32_e32 v115, v117
	v_lshlrev_b32_e32 v8, 16, v121
	v_and_b32_e32 v9, 0xffff0000, v121
	v_pk_mul_f32 v[120:121], v[54:55], v[54:55]
	v_pk_add_f32 v[148:149], v[152:153], v[154:155]
	v_pk_add_f32 v[114:115], v[114:115], v[118:119]
	v_pk_fma_f32 v[120:121], v[56:57], v[56:57], v[120:121]
	v_pk_add_f32 v[114:115], v[114:115], v[148:149]
	v_pk_mul_f32 v[130:131], v[48:49], v[48:49]
	v_pk_add_f32 v[120:121], v[120:121], v[120:121] op_sel:[0,1] op_sel_hi:[1,0]
	v_pk_add_f32 v[114:115], v[114:115], v[114:115] op_sel:[0,1] op_sel_hi:[1,0]
	v_mul_f32_e32 v86, v43, v43
	v_mov_b32_e32 v141, v41
	v_pk_fma_f32 v[130:131], v[50:51], v[50:51], v[130:131]
	v_mov_b32_e32 v140, v120
	v_mov_b32_e32 v40, v114
	v_mul_f32_e32 v168, v37, v37
	v_mul_f32_e32 v169, v34, v34
	v_mul_f32_e32 v170, v35, v35
	v_pk_fma_f32 v[156:157], v[42:43], v[42:43], v[86:87] op_sel_hi:[1,1,0]
	v_pk_add_f32 v[130:131], v[130:131], v[130:131] op_sel:[0,1] op_sel_hi:[1,0]
	v_pk_add_f32 v[114:115], v[114:115], v[120:121]
	v_pk_mul_f32 v[116:117], v[40:41], v[140:141]
	v_mov_b32_e32 v157, v169
	v_mov_b32_e32 v159, v170
	v_mov_b32_e32 v131, v168
	v_mov_b32_e32 v115, v117
	v_pk_mul_f32 v[132:133], v[28:29], v[28:29]
	v_pk_add_f32 v[150:151], v[156:157], v[158:159]
	v_pk_add_f32 v[114:115], v[114:115], v[130:131]
	v_pk_fma_f32 v[132:133], v[32:33], v[32:33], v[132:133]
	v_pk_add_f32 v[114:115], v[114:115], v[150:151]
	v_pk_mul_f32 v[134:135], v[22:23], v[22:23]
	v_pk_add_f32 v[132:133], v[132:133], v[132:133] op_sel:[0,1] op_sel_hi:[1,0]
	v_pk_add_f32 v[114:115], v[114:115], v[114:115] op_sel:[0,1] op_sel_hi:[1,0]
	v_mov_b32_e32 v143, v13
	v_pk_fma_f32 v[134:135], v[24:25], v[24:25], v[134:135]
	v_mov_b32_e32 v142, v132
	v_mov_b32_e32 v12, v114
	v_mul_f32_e32 v171, v11, v11
	v_mul_f32_e32 v172, v8, v8
	v_mul_f32_e32 v173, v9, v9
	v_pk_add_f32 v[134:135], v[134:135], v[134:135] op_sel:[0,1] op_sel_hi:[1,0]
	v_pk_add_f32 v[114:115], v[114:115], v[132:133]
	v_pk_mul_f32 v[116:117], v[12:13], v[142:143]
	v_mov_b32_e32 v161, v172
	v_mov_b32_e32 v163, v173
	v_mov_b32_e32 v135, v171
	v_mov_b32_e32 v115, v117
	v_pk_add_f32 v[152:153], v[160:161], v[162:163]
	v_pk_add_f32 v[114:115], v[114:115], v[134:135]
	s_waitcnt vmcnt(15)
	v_lshlrev_b32_e32 v136, 16, v122
	v_pk_add_f32 v[114:115], v[114:115], v[152:153]
	v_and_b32_e32 v137, 0xffff0000, v122
	v_add_f32_e32 v10, v114, v115
	ds_bpermute_b32 v12, v100, v10
	v_lshlrev_b32_e32 v122, 16, v123
	v_and_b32_e32 v123, 0xffff0000, v123
	v_mov_b32_e32 v86, v91
	s_waitcnt lgkmcnt(0)
	v_add_f32_e32 v10, v10, v12
	ds_bpermute_b32 v12, v101, v10
	s_waitcnt lgkmcnt(0)
	v_add_f32_e32 v10, v10, v12
	ds_bpermute_b32 v12, v102, v10
	s_waitcnt lgkmcnt(0)
	v_add_f32_e32 v10, v10, v12
	ds_bpermute_b32 v12, v103, v10
	s_waitcnt lgkmcnt(0)
	v_add_f32_e32 v10, v10, v12
	ds_bpermute_b32 v12, v104, v10
	s_waitcnt lgkmcnt(0)
	v_add_f32_e32 v10, v10, v12
	ds_bpermute_b32 v12, v105, v10
	s_waitcnt lgkmcnt(0)
	v_add_f32_e32 v10, v10, v12
	v_fmamk_f32 v10, v10, 0x39800000, v106
	v_mul_f32_e32 v12, 0x4f800000, v10
	v_cmp_gt_f32_e32 vcc, s47, v10
	s_nop 1
	v_cndmask_b32_e32 v10, v10, v12, vcc
	v_sqrt_f32_e32 v12, v10
	s_nop 0
	v_add_u32_e32 v36, -1, v12
	v_add_u32_e32 v40, 1, v12
	v_fma_f32 v62, -v36, v12, v10
	v_fma_f32 v64, -v40, v12, v10
	v_cmp_ge_f32_e64 s[0:1], 0, v62
	s_nop 1
	v_cndmask_b32_e64 v12, v12, v36, s[0:1]
	v_cmp_lt_f32_e64 s[0:1], 0, v64
	s_nop 1
	v_cndmask_b32_e64 v12, v12, v40, s[0:1]
	v_mul_f32_e32 v36, 0x37800000, v12
	v_cndmask_b32_e32 v12, v12, v36, vcc
	v_cmp_class_f32_e32 vcc, v10, v107
	s_nop 1
	v_cndmask_b32_e32 v10, v12, v10, vcc
	v_div_scale_f32 v12, s[0:1], v10, v10, 0.5
	v_rcp_f32_e32 v40, v12
	v_div_scale_f32 v36, vcc, 0.5, v10, 0.5
	v_fma_f32 v62, -v12, v40, 1.0
	v_fmac_f32_e32 v40, v62, v40
	v_mul_f32_e32 v62, v36, v40
	v_fma_f32 v64, -v12, v62, v36
	v_fmac_f32_e32 v62, v64, v40
	v_fma_f32 v12, -v12, v62, v36
	v_div_fmas_f32 v12, v12, v40, v62
	v_div_fixup_f32 v12, v12, v10, 0.5
	v_pk_mul_f32 v[114:115], v[12:13], v[124:125] op_sel_hi:[0,1]
	v_pk_mul_f32 v[112:113], v[12:13], v[112:113] op_sel_hi:[0,1]
	v_pk_mul_f32 v[0:1], v[112:113], v[0:1]
	v_pk_mul_f32 v[2:3], v[114:115], v[2:3]
	s_waitcnt vmcnt(0) lgkmcnt(0)
	v_pk_fma_f32 v[0:1], v[0:1], v[108:109], v[136:137]
	v_pk_fma_f32 v[2:3], v[2:3], v[110:111], v[122:123]
	buffer_store_dwordx4 v[0:3], v98, s[8:11], 0 offen nt
	s_nop 0
	ds_read_b128 v[0:3], v98 offset:1024
	s_nop 0
	ds_read_b128 v[108:111], v174 offset:1024
	v_mov_b32_e32 v112, v126
	v_mov_b32_e32 v113, v128
	v_mov_b32_e32 v128, v127
	v_pk_mul_f32 v[112:113], v[12:13], v[112:113] op_sel_hi:[0,1]
	v_pk_mul_f32 v[116:117], v[12:13], v[128:129] op_sel_hi:[0,1]
	v_lshlrev_b32_e32 v114, 16, v96
	v_and_b32_e32 v115, 0xffff0000, v96
	v_lshlrev_b32_e32 v96, 16, v97
	v_and_b32_e32 v97, 0xffff0000, v97
	v_pk_mul_f32 v[92:93], v[12:13], v[92:93] op_sel_hi:[0,1]
	v_pk_mul_f32 v[94:95], v[12:13], v[94:95] op_sel_hi:[0,1]
	v_pk_mul_f32 v[86:87], v[12:13], v[86:87] op_sel_hi:[0,1]
	v_pk_mul_f32 v[84:85], v[12:13], v[84:85] op_sel_hi:[0,1]
	v_pk_mul_f32 v[68:69], v[12:13], v[68:69] op_sel_hi:[0,1]
	v_pk_mul_f32 v[70:71], v[12:13], v[70:71] op_sel_hi:[0,1]
	v_mov_b32_e32 v62, v65
	v_pk_mul_f32 v[62:63], v[12:13], v[62:63] op_sel_hi:[0,1]
	v_pk_mul_f32 v[60:61], v[12:13], v[60:61] op_sel_hi:[0,1]
	v_pk_mul_f32 v[42:43], v[12:13], v[42:43] op_sel_hi:[0,1]
	v_pk_mul_f32 v[44:45], v[12:13], v[44:45] op_sel_hi:[0,1]
	v_mov_b32_e32 v36, v41
	v_pk_mul_f32 v[36:37], v[12:13], v[36:37] op_sel_hi:[0,1]
	v_pk_mul_f32 v[34:35], v[12:13], v[34:35] op_sel_hi:[0,1]
	v_pk_mul_f32 v[18:19], v[12:13], v[18:19] op_sel_hi:[0,1]
	v_pk_mul_f32 v[20:21], v[12:13], v[20:21] op_sel_hi:[0,1]
	v_mov_b32_e32 v10, v13
	v_pk_mul_f32 v[10:11], v[12:13], v[10:11] op_sel_hi:[0,1]
	v_pk_mul_f32 v[8:9], v[12:13], v[8:9] op_sel_hi:[0,1]
	s_waitcnt lgkmcnt(1)
	v_pk_mul_f32 v[2:3], v[116:117], v[2:3]
	v_pk_mul_f32 v[0:1], v[112:113], v[0:1]
	s_waitcnt lgkmcnt(0)
	v_pk_fma_f32 v[2:3], v[2:3], v[110:111], v[96:97]
	v_pk_fma_f32 v[0:1], v[0:1], v[108:109], v[114:115]
	buffer_store_dwordx4 v[0:3], v98, s[8:11], s31 offen nt
	s_nop 0
	ds_read_b128 v[0:3], v98 offset:2048
	s_nop 0
	ds_read_b128 v[108:111], v174 offset:2048
	v_lshlrev_b32_e32 v96, 16, v88
	v_and_b32_e32 v97, 0xffff0000, v88
	v_lshlrev_b32_e32 v88, 16, v89
	v_and_b32_e32 v89, 0xffff0000, v89
	s_waitcnt lgkmcnt(1)
	v_pk_mul_f32 v[2:3], v[94:95], v[2:3]
	v_pk_mul_f32 v[0:1], v[92:93], v[0:1]
	s_waitcnt lgkmcnt(0)
	v_pk_fma_f32 v[2:3], v[2:3], v[110:111], v[88:89]
	v_pk_fma_f32 v[0:1], v[0:1], v[108:109], v[96:97]
	buffer_store_dwordx4 v[0:3], v98, s[8:11], s35 offen nt
	s_nop 0
	ds_read_b128 v[0:3], v98 offset:3072
	s_nop 0
	ds_read_b128 v[92:95], v174 offset:3072
	v_lshlrev_b32_e32 v88, 16, v80
	v_and_b32_e32 v89, 0xffff0000, v80
	v_lshlrev_b32_e32 v80, 16, v81
	v_and_b32_e32 v81, 0xffff0000, v81
	s_waitcnt lgkmcnt(1)
	v_pk_mul_f32 v[2:3], v[84:85], v[2:3]
	v_pk_mul_f32 v[0:1], v[86:87], v[0:1]
	s_waitcnt lgkmcnt(0)
	v_pk_fma_f32 v[2:3], v[2:3], v[94:95], v[80:81]
	v_pk_fma_f32 v[0:1], v[0:1], v[92:93], v[88:89]
	buffer_store_dwordx4 v[0:3], v98, s[8:11], s37 offen nt
	s_nop 0
	ds_read_b128 v[0:3], v98 offset:4096
	s_nop 0
	ds_read_b128 v[84:87], v174 offset:4096
	v_mov_b32_e32 v80, v82
	v_mov_b32_e32 v81, v78
	v_mov_b32_e32 v78, v83
	v_pk_mul_f32 v[80:81], v[12:13], v[80:81] op_sel_hi:[0,1]
	v_pk_mul_f32 v[78:79], v[12:13], v[78:79] op_sel_hi:[0,1]
	v_lshlrev_b32_e32 v82, 16, v72
	v_and_b32_e32 v83, 0xffff0000, v72
	v_lshlrev_b32_e32 v72, 16, v73
	v_and_b32_e32 v73, 0xffff0000, v73
	s_waitcnt lgkmcnt(1)
	v_pk_mul_f32 v[2:3], v[78:79], v[2:3]
	v_pk_mul_f32 v[0:1], v[80:81], v[0:1]
	s_waitcnt lgkmcnt(0)
	v_pk_fma_f32 v[2:3], v[2:3], v[86:87], v[72:73]
	v_pk_fma_f32 v[0:1], v[0:1], v[84:85], v[82:83]
	buffer_store_dwordx4 v[0:3], v98, s[8:11], s39 offen nt
	s_nop 0
	ds_read_b128 v[0:3], v98 offset:5120
	s_nop 0
	ds_read_b128 v[78:81], v174 offset:5120
	v_mov_b32_e32 v72, v76
	v_mov_b32_e32 v73, v74
	v_mov_b32_e32 v74, v77
	v_pk_mul_f32 v[72:73], v[12:13], v[72:73] op_sel_hi:[0,1]
	v_pk_mul_f32 v[74:75], v[12:13], v[74:75] op_sel_hi:[0,1]
	v_lshlrev_b32_e32 v76, 16, v66
	v_and_b32_e32 v77, 0xffff0000, v66
	v_lshlrev_b32_e32 v66, 16, v67
	v_and_b32_e32 v67, 0xffff0000, v67
	s_waitcnt lgkmcnt(1)
	v_pk_mul_f32 v[2:3], v[74:75], v[2:3]
	v_pk_mul_f32 v[0:1], v[72:73], v[0:1]
	s_waitcnt lgkmcnt(0)
	v_pk_fma_f32 v[2:3], v[2:3], v[80:81], v[66:67]
	v_pk_fma_f32 v[0:1], v[0:1], v[78:79], v[76:77]
	buffer_store_dwordx4 v[0:3], v98, s[8:11], s41 offen nt
	s_nop 0
	ds_read_b128 v[0:3], v98 offset:6144
	s_nop 0
	ds_read_b128 v[72:75], v174 offset:6144
	v_lshlrev_b32_e32 v66, 16, v58
	v_and_b32_e32 v67, 0xffff0000, v58
	v_lshlrev_b32_e32 v58, 16, v59
	v_and_b32_e32 v59, 0xffff0000, v59
	s_waitcnt lgkmcnt(1)
	v_pk_mul_f32 v[2:3], v[70:71], v[2:3]
	v_pk_mul_f32 v[0:1], v[68:69], v[0:1]
	s_waitcnt lgkmcnt(0)
	v_pk_fma_f32 v[2:3], v[2:3], v[74:75], v[58:59]
	v_pk_fma_f32 v[0:1], v[0:1], v[72:73], v[66:67]
	buffer_store_dwordx4 v[0:3], v98, s[8:11], s43 offen nt
	s_nop 0
	ds_read_b128 v[0:3], v98 offset:7168
	s_nop 0
	ds_read_b128 v[66:69], v174 offset:7168
	v_lshlrev_b32_e32 v58, 16, v52
	v_and_b32_e32 v59, 0xffff0000, v52
	v_lshlrev_b32_e32 v52, 16, v53
	v_and_b32_e32 v53, 0xffff0000, v53
	s_waitcnt lgkmcnt(1)
	v_pk_mul_f32 v[2:3], v[60:61], v[2:3]
	v_pk_mul_f32 v[0:1], v[62:63], v[0:1]
	s_waitcnt lgkmcnt(0)
	v_pk_fma_f32 v[2:3], v[2:3], v[68:69], v[52:53]
	v_pk_fma_f32 v[0:1], v[0:1], v[66:67], v[58:59]
	buffer_store_dwordx4 v[0:3], v98, s[8:11], s45 offen nt
	s_nop 0
	ds_read_b128 v[0:3], v98 offset:8192
	s_nop 0
	ds_read_b128 v[58:61], v174 offset:8192
	v_mov_b32_e32 v52, v56
	v_mov_b32_e32 v53, v54
	v_mov_b32_e32 v54, v57
	v_pk_mul_f32 v[52:53], v[12:13], v[52:53] op_sel_hi:[0,1]
	v_pk_mul_f32 v[54:55], v[12:13], v[54:55] op_sel_hi:[0,1]
	v_lshlrev_b32_e32 v56, 16, v46
	v_and_b32_e32 v57, 0xffff0000, v46
	v_lshlrev_b32_e32 v46, 16, v47
	v_and_b32_e32 v47, 0xffff0000, v47
	s_waitcnt lgkmcnt(1)
	v_pk_mul_f32 v[2:3], v[54:55], v[2:3]
	v_pk_mul_f32 v[0:1], v[52:53], v[0:1]
	s_waitcnt lgkmcnt(0)
	v_pk_fma_f32 v[2:3], v[2:3], v[60:61], v[46:47]
	v_pk_fma_f32 v[0:1], v[0:1], v[58:59], v[56:57]
	buffer_store_dwordx4 v[0:3], v98, s[8:11], s2 offen nt
	s_nop 0
	ds_read_b128 v[0:3], v98 offset:9216
	s_nop 0
	ds_read_b128 v[52:55], v174 offset:9216
	v_mov_b32_e32 v46, v50
	v_mov_b32_e32 v47, v48
	v_mov_b32_e32 v48, v51
	v_pk_mul_f32 v[46:47], v[12:13], v[46:47] op_sel_hi:[0,1]
	v_pk_mul_f32 v[48:49], v[12:13], v[48:49] op_sel_hi:[0,1]
	v_lshlrev_b32_e32 v50, 16, v38
	v_and_b32_e32 v51, 0xffff0000, v38
	v_lshlrev_b32_e32 v38, 16, v39
	v_and_b32_e32 v39, 0xffff0000, v39
	s_waitcnt lgkmcnt(1)
	v_pk_mul_f32 v[2:3], v[48:49], v[2:3]
	v_pk_mul_f32 v[0:1], v[46:47], v[0:1]
	s_waitcnt lgkmcnt(0)
	v_pk_fma_f32 v[2:3], v[2:3], v[54:55], v[38:39]
	v_pk_fma_f32 v[0:1], v[0:1], v[52:53], v[50:51]
	buffer_store_dwordx4 v[0:3], v98, s[8:11], s48 offen nt
	s_nop 0
	ds_read_b128 v[0:3], v98 offset:10240
	s_nop 0
	ds_read_b128 v[46:49], v174 offset:10240
	v_lshlrev_b32_e32 v38, 16, v30
	v_and_b32_e32 v39, 0xffff0000, v30
	v_lshlrev_b32_e32 v30, 16, v31
	v_and_b32_e32 v31, 0xffff0000, v31
	s_waitcnt lgkmcnt(1)
	v_pk_mul_f32 v[2:3], v[44:45], v[2:3]
	v_pk_mul_f32 v[0:1], v[42:43], v[0:1]
	s_waitcnt lgkmcnt(0)
	v_pk_fma_f32 v[2:3], v[2:3], v[48:49], v[30:31]
	v_pk_fma_f32 v[0:1], v[0:1], v[46:47], v[38:39]
	buffer_store_dwordx4 v[0:3], v98, s[8:11], s49 offen nt
	s_nop 0
	ds_read_b128 v[0:3], v98 offset:11264
	s_nop 0
	ds_read_b128 v[42:45], v174 offset:11264
	v_lshlrev_b32_e32 v30, 16, v26
	v_and_b32_e32 v31, 0xffff0000, v26
	v_lshlrev_b32_e32 v26, 16, v27
	v_and_b32_e32 v27, 0xffff0000, v27
	s_waitcnt lgkmcnt(1)
	v_pk_mul_f32 v[2:3], v[34:35], v[2:3]
	v_pk_mul_f32 v[0:1], v[36:37], v[0:1]
	s_waitcnt lgkmcnt(0)
	v_pk_fma_f32 v[2:3], v[2:3], v[44:45], v[26:27]
	v_pk_fma_f32 v[0:1], v[0:1], v[42:43], v[30:31]
	buffer_store_dwordx4 v[0:3], v98, s[8:11], s50 offen nt
	s_nop 0
	ds_read_b128 v[0:3], v98 offset:12288
	s_nop 0
	ds_read_b128 v[34:37], v174 offset:12288
	v_mov_b32_e32 v26, v32
	v_mov_b32_e32 v27, v28
	v_mov_b32_e32 v28, v33
	v_pk_mul_f32 v[26:27], v[12:13], v[26:27] op_sel_hi:[0,1]
	v_pk_mul_f32 v[28:29], v[12:13], v[28:29] op_sel_hi:[0,1]
	v_lshlrev_b32_e32 v30, 16, v16
	v_and_b32_e32 v31, 0xffff0000, v16
	v_lshlrev_b32_e32 v16, 16, v17
	v_and_b32_e32 v17, 0xffff0000, v17
	s_waitcnt lgkmcnt(1)
	v_pk_mul_f32 v[2:3], v[28:29], v[2:3]
	v_pk_mul_f32 v[0:1], v[26:27], v[0:1]
	s_waitcnt lgkmcnt(0)
	v_pk_fma_f32 v[2:3], v[2:3], v[36:37], v[16:17]
	v_pk_fma_f32 v[0:1], v[0:1], v[34:35], v[30:31]
	buffer_store_dwordx4 v[0:3], v98, s[8:11], s51 offen nt
	s_nop 0
	ds_read_b128 v[0:3], v98 offset:13312
	s_nop 0
	ds_read_b128 v[26:29], v174 offset:13312
	v_mov_b32_e32 v16, v24
	v_mov_b32_e32 v17, v22
	v_mov_b32_e32 v22, v25
	v_pk_mul_f32 v[16:17], v[12:13], v[16:17] op_sel_hi:[0,1]
	v_pk_mul_f32 v[22:23], v[12:13], v[22:23] op_sel_hi:[0,1]
	v_lshlrev_b32_e32 v24, 16, v14
	v_and_b32_e32 v25, 0xffff0000, v14
	v_lshlrev_b32_e32 v14, 16, v15
	v_and_b32_e32 v15, 0xffff0000, v15
	s_waitcnt lgkmcnt(1)
	v_pk_mul_f32 v[2:3], v[22:23], v[2:3]
	v_pk_mul_f32 v[0:1], v[16:17], v[0:1]
	s_waitcnt lgkmcnt(0)
	v_pk_fma_f32 v[2:3], v[2:3], v[28:29], v[14:15]
	v_pk_fma_f32 v[0:1], v[0:1], v[26:27], v[24:25]
	buffer_store_dwordx4 v[0:3], v98, s[8:11], s52 offen nt
	s_nop 0
	ds_read_b128 v[0:3], v98 offset:14336
	s_nop 0
	ds_read_b128 v[14:17], v174 offset:14336
	v_lshlrev_b32_e32 v22, 16, v6
	v_and_b32_e32 v23, 0xffff0000, v6
	v_lshlrev_b32_e32 v6, 16, v7
	v_and_b32_e32 v7, 0xffff0000, v7
	s_waitcnt lgkmcnt(1)
	v_pk_mul_f32 v[2:3], v[20:21], v[2:3]
	v_pk_mul_f32 v[0:1], v[18:19], v[0:1]
	s_waitcnt lgkmcnt(0)
	v_pk_fma_f32 v[2:3], v[2:3], v[16:17], v[6:7]
	v_pk_fma_f32 v[0:1], v[0:1], v[14:15], v[22:23]
	buffer_store_dwordx4 v[0:3], v98, s[8:11], s53 offen nt
	s_nop 0
	ds_read_b128 v[0:3], v98 offset:15360
	s_nop 0
	ds_read_b128 v[14:17], v174 offset:15360
	v_lshlrev_b32_e32 v6, 16, v4
	v_and_b32_e32 v7, 0xffff0000, v4
	v_lshlrev_b32_e32 v4, 16, v5
	v_and_b32_e32 v5, 0xffff0000, v5
	s_waitcnt lgkmcnt(1)
	v_pk_mul_f32 v[2:3], v[8:9], v[2:3]
	v_pk_mul_f32 v[0:1], v[10:11], v[0:1]
	s_waitcnt lgkmcnt(0)
	v_pk_fma_f32 v[2:3], v[2:3], v[16:17], v[4:5]
	v_pk_fma_f32 v[0:1], v[0:1], v[14:15], v[6:7]
	buffer_store_dwordx4 v[0:3], v98, s[8:11], s54 offen nt
	s_cbranch_scc1 .LBB0_922
